# pool rewrite + prologue x-to-hbf row loop de-serialised (3 rows of loads issued up front, 4th as soon as registers free, exact counted vmcnt)
# baseline (speedup 1.0000x reference)
; __device__ __forceinline__ unsigned cvt_pk_bf16(float lo, float hi) { unsigned r; asm volatile("v_cvt_pk_bf16_f32 %0, %1, %2" : "=v"(r) : "v"(lo), "v"(hi)); return r; }
; __device__ void phase_prep(float* ldsf) {
;     ...
;     float4 gq[8];
; #pragma unroll
;     for (int i = 0; i < 8; ++i) gq[i] = ((const float4*)g0)[i * 64 + lane];
;     for (int row = blockIdx.x * 8 + wave; row < M_TOK; row += gridDim.x * 8) {
;         const float4* xr = (const float4*)(x + (size_t)row * DM);
;         float4 xv[8];
; #pragma unroll
;         for (int i = 0; i < 8; ++i) xv[i] = xr[i * 64 + lane];
;         float ss = 0.f;
; #pragma unroll
;         for (int i = 0; i < 8; ++i) { const int idx = i * 64 + lane; const float4 v = xv[i];
;             ss += (v.x * v.x + v.y * v.y) + (v.z * v.z + v.w * v.w);
;             u32x2 w; w.x = cvt_pk_bf16(v.x * gq[i].x, v.y * gq[i].y); w.y = cvt_pk_bf16(v.z * gq[i].z, v.w * gq[i].w);
;             *(u32x2*)(hbf + (size_t)row * DM + idx * 4) = w; }
; #pragma unroll
;         for (int o = 32; o >= 1; o >>= 1) ss += __shfl_xor(ss, o);
;         if (lane == 0) rowss[row] = ss;
.LBB0_78:
	s_waitcnt vmcnt(6)
	v_ashrrev_i32_e32 v2, 6, v1
	v_lshl_add_u32 v34, s67, 3, v2
	s_movk_i32 s14, 0x2000
	v_cmp_gt_i32_e32 vcc, s14, v34
	s_and_saveexec_b64 s[14:15], vcc
	s_cbranch_execz .LBB0_83
	v_and_b32_e32 v40, 63, v1
	v_lshlrev_b32_e32 v1, 4, v40
	v_or_b32_e32 v42, 0x100, v40
	global_load_dwordx4 v[2:5], v1, s[10:11]
	global_load_dwordx4 v[6:9], v1, s[10:11] offset:1024
	global_load_dwordx4 v[10:13], v1, s[10:11] offset:2048
	global_load_dwordx4 v[14:17], v1, s[10:11] offset:3072
	v_lshlrev_b32_e32 v1, 4, v42
	v_or_b32_e32 v44, 0x140, v40
	v_or_b32_e32 v46, 0x180, v40
	s_waitcnt vmcnt(4)
	v_lshlrev_b32_e32 v26, 4, v44
	global_load_dwordx4 v[18:21], v1, s[10:11]
	global_load_dwordx4 v[22:25], v26, s[10:11]
	v_lshlrev_b32_e32 v1, 4, v46
	v_or_b32_e32 v48, 0x1c0, v40
	v_lshlrev_b32_e32 v35, 4, v48
	global_load_dwordx4 v[26:29], v1, s[10:11]
	global_load_dwordx4 v[30:33], v35, s[10:11]
	v_mbcnt_lo_u32_b32 v1, -1, 0
	v_mbcnt_hi_u32_b32 v1, -1, v1
	v_mov_b32_e32 v37, 0
	v_lshlrev_b32_e32 v36, 3, v40
	v_and_b32_e32 v35, 64, v1
	v_cmp_eq_u32_e32 vcc, 0, v40
	v_lshl_add_u64 v[38:39], s[4:5], 0, v[36:37]
	s_lshl_b32 s16, s68, 3
	s_mov_b64 s[10:11], 0
	v_lshlrev_b32_e32 v36, 4, v40
	v_lshlrev_b32_e32 v40, 4, v42
	v_lshlrev_b32_e32 v42, 4, v44
	v_lshlrev_b32_e32 v44, 4, v46
	v_lshlrev_b32_e32 v46, 4, v48
	s_movk_i32 s17, 0x1fff
	v_mov_b32_e32 v41, v37
	v_mov_b32_e32 v43, v37
	v_mov_b32_e32 v45, v37
	v_mov_b32_e32 v47, v37
	v_add_u32_e32 v48, 64, v35
	v_xor_b32_e32 v49, 32, v1
	v_xor_b32_e32 v50, 16, v1
	v_xor_b32_e32 v51, 8, v1
	v_xor_b32_e32 v52, 4, v1
	v_xor_b32_e32 v53, 2, v1
	v_xor_b32_e32 v54, 1, v1
	s_cmp_lg_u32 s68, 0x100
	s_cbranch_scc1 .LBB0_81
	s_waitcnt lgkmcnt(0)
	v_add_u32_e32 v220, 0x0, v34
	v_mov_b32_e32 v221, 0
	v_lshlrev_b64 v[56:57], 13, v[220:221]
	v_lshl_add_u64 v[84:85], s[8:9], 0, v[56:57]
	v_lshl_add_u64 v[72:73], v[84:85], 0, v[36:37]
	global_load_dwordx4 v[56:59], v[72:73], off
	global_load_dwordx4 v[60:63], v[72:73], off offset:1024
	global_load_dwordx4 v[64:67], v[72:73], off offset:2048
	global_load_dwordx4 v[68:71], v[72:73], off offset:3072
	v_lshl_add_u64 v[72:73], v[84:85], 0, v[40:41]
	global_load_dwordx4 v[72:75], v[72:73], off
	v_lshl_add_u64 v[76:77], v[84:85], 0, v[42:43]
	global_load_dwordx4 v[76:79], v[76:77], off
	v_lshl_add_u64 v[80:81], v[84:85], 0, v[44:45]
	global_load_dwordx4 v[80:83], v[80:81], off
	v_lshl_add_u64 v[84:85], v[84:85], 0, v[46:47]
	global_load_dwordx4 v[84:87], v[84:85], off
	v_add_u32_e32 v220, 0x800, v34
	v_mov_b32_e32 v221, 0
	v_lshlrev_b64 v[156:157], 13, v[220:221]
	v_lshl_add_u64 v[184:185], s[8:9], 0, v[156:157]
	v_lshl_add_u64 v[172:173], v[184:185], 0, v[36:37]
	global_load_dwordx4 v[156:159], v[172:173], off
	global_load_dwordx4 v[160:163], v[172:173], off offset:1024
	global_load_dwordx4 v[164:167], v[172:173], off offset:2048
	global_load_dwordx4 v[168:171], v[172:173], off offset:3072
	v_lshl_add_u64 v[172:173], v[184:185], 0, v[40:41]
	global_load_dwordx4 v[172:175], v[172:173], off
	v_lshl_add_u64 v[176:177], v[184:185], 0, v[42:43]
	global_load_dwordx4 v[176:179], v[176:177], off
	v_lshl_add_u64 v[180:181], v[184:185], 0, v[44:45]
	global_load_dwordx4 v[180:183], v[180:181], off
	v_lshl_add_u64 v[184:185], v[184:185], 0, v[46:47]
	global_load_dwordx4 v[184:187], v[184:185], off
	v_add_u32_e32 v220, 0x1000, v34
	v_mov_b32_e32 v221, 0
	v_lshlrev_b64 v[188:189], 13, v[220:221]
	v_lshl_add_u64 v[216:217], s[8:9], 0, v[188:189]
	v_lshl_add_u64 v[204:205], v[216:217], 0, v[36:37]
	global_load_dwordx4 v[188:191], v[204:205], off
	global_load_dwordx4 v[192:195], v[204:205], off offset:1024
	global_load_dwordx4 v[196:199], v[204:205], off offset:2048
	global_load_dwordx4 v[200:203], v[204:205], off offset:3072
	v_lshl_add_u64 v[204:205], v[216:217], 0, v[40:41]
	global_load_dwordx4 v[204:207], v[204:205], off
	v_lshl_add_u64 v[208:209], v[216:217], 0, v[42:43]
	global_load_dwordx4 v[208:211], v[208:209], off
	v_lshl_add_u64 v[212:213], v[216:217], 0, v[44:45]
	global_load_dwordx4 v[212:215], v[212:213], off
	v_lshl_add_u64 v[216:217], v[216:217], 0, v[46:47]
	global_load_dwordx4 v[216:219], v[216:217], off
	v_add_u32_e32 v222, 0x0, v34
	v_mov_b32_e32 v223, 0
	v_lshlrev_b64 v[88:89], 12, v[222:223]
	v_lshl_add_u64 v[88:89], v[38:39], 0, v[88:89]
	v_cmp_lt_i32_e64 s[4:5], v49, v48
	s_waitcnt vmcnt(23)
	v_mul_f32_e32 v55, v57, v57
	v_mul_f32_e32 v90, v59, v59
	s_waitcnt vmcnt(22)
	v_mul_f32_e32 v93, v61, v61
	v_mul_f32_e32 v94, v63, v63
	s_waitcnt vmcnt(21)
	v_mul_f32_e32 v97, v65, v65
	v_mul_f32_e32 v98, v67, v67
	v_fmac_f32_e32 v55, v56, v56
	v_fmac_f32_e32 v90, v58, v58
	v_fmac_f32_e32 v93, v60, v60
	v_fmac_f32_e32 v94, v62, v62
	v_mul_f32_e32 v91, v2, v56
	v_mul_f32_e32 v57, v3, v57
	v_mul_f32_e32 v92, v4, v58
	v_mul_f32_e32 v59, v5, v59
	s_waitcnt vmcnt(20)
	v_mul_f32_e32 v101, v69, v69
	v_mul_f32_e32 v102, v71, v71
	v_fmac_f32_e32 v97, v64, v64
	v_fmac_f32_e32 v98, v66, v66
	v_cvt_pk_bf16_f32 v56, v91, v57
	v_add_f32_e32 v55, v55, v90
	v_add_f32_e32 v58, v93, v94
	v_mul_f32_e32 v95, v6, v60
	v_mul_f32_e32 v61, v7, v61
	s_waitcnt vmcnt(19)
	v_mul_f32_e32 v105, v73, v73
	v_mul_f32_e32 v106, v75, v75
	v_fmac_f32_e32 v101, v68, v68
	v_fmac_f32_e32 v102, v70, v70
	v_cvt_pk_bf16_f32 v57, v92, v59
	global_store_dwordx2 v[88:89], v[56:57], off
	v_cvt_pk_bf16_f32 v56, v95, v61
	v_add_f32_e32 v59, v97, v98
	v_add_f32_e32 v55, v55, v58
	v_mul_f32_e32 v96, v8, v62
	v_mul_f32_e32 v63, v9, v63
	v_mul_f32_e32 v99, v10, v64
	v_mul_f32_e32 v65, v11, v65
	s_waitcnt vmcnt(19)
; __device__ __forceinline__ unsigned cvt_pk_bf16(float lo, float hi) { unsigned r; asm volatile("v_cvt_pk_bf16_f32 %0, %1, %2" : "=v"(r) : "v"(lo), "v"(hi)); return r; }
; __device__ void phase_prep(float* ldsf) {
;     ...
;     for (int row = blockIdx.x * 8 + wave; row < M_TOK; row += gridDim.x * 8) {
;         const float4* xr = (const float4*)(x + (size_t)row * DM);
;         float4 xv[8];
; #pragma unroll
;         for (int i = 0; i < 8; ++i) xv[i] = xr[i * 64 + lane];
;         float ss = 0.f;
; #pragma unroll
;         for (int i = 0; i < 8; ++i) { const int idx = i * 64 + lane; const float4 v = xv[i];
;             ss += (v.x * v.x + v.y * v.y) + (v.z * v.z + v.w * v.w);
;             u32x2 w; w.x = cvt_pk_bf16(v.x * gq[i].x, v.y * gq[i].y); w.y = cvt_pk_bf16(v.z * gq[i].z, v.w * gq[i].w);
;             *(u32x2*)(hbf + (size_t)row * DM + idx * 4) = w; }
; #pragma unroll
;         for (int o = 32; o >= 1; o >>= 1) ss += __shfl_xor(ss, o);
;         if (lane == 0) rowss[row] = ss;
	v_mul_f32_e32 v109, v77, v77
	v_mul_f32_e32 v110, v79, v79
	v_fmac_f32_e32 v105, v72, v72
	v_fmac_f32_e32 v106, v74, v74
	v_cvt_pk_bf16_f32 v57, v96, v63
	v_add_f32_e32 v60, v101, v102
	global_store_dwordx2 v[88:89], v[56:57], off offset:512
	v_cvt_pk_bf16_f32 v56, v99, v65
	v_add_f32_e32 v55, v55, v59
	v_mul_f32_e32 v100, v12, v66
	v_mul_f32_e32 v67, v13, v67
	v_mul_f32_e32 v103, v14, v68
	v_mul_f32_e32 v69, v15, v69
	s_waitcnt vmcnt(19)
	v_mul_f32_e32 v111, v81, v81
	v_mul_f32_e32 v112, v83, v83
	v_fmac_f32_e32 v109, v76, v76
	v_fmac_f32_e32 v110, v78, v78
	v_add_f32_e32 v61, v105, v106
	v_cvt_pk_bf16_f32 v57, v100, v67
	global_store_dwordx2 v[88:89], v[56:57], off offset:1024
	v_cvt_pk_bf16_f32 v56, v103, v69
	v_add_f32_e32 v55, v55, v60
	v_mul_f32_e32 v104, v16, v70
	v_mul_f32_e32 v71, v17, v71
	s_waitcnt vmcnt(19)
	v_mul_f32_e32 v113, v85, v85
	v_fmac_f32_e32 v111, v80, v80
	v_fmac_f32_e32 v112, v82, v82
	v_add_f32_e32 v62, v109, v110
	v_cvt_pk_bf16_f32 v57, v104, v71
	global_store_dwordx2 v[88:89], v[56:57], off offset:1536
	v_add_f32_e32 v55, v55, v61
	v_mul_f32_e32 v56, v87, v87
	v_fmac_f32_e32 v113, v84, v84
	v_add_f32_e32 v63, v111, v112
	v_add_f32_e32 v55, v55, v62
	v_fmac_f32_e32 v56, v86, v86
	v_add_f32_e32 v55, v55, v63
	v_add_f32_e32 v56, v113, v56
	v_add_f32_e32 v55, v55, v56
	v_cndmask_b32_e64 v56, v1, v49, s[4:5]
	v_lshlrev_b32_e32 v56, 2, v56
	ds_bpermute_b32 v58, v56, v55
	v_mul_f32_e32 v107, v18, v72
	v_mul_f32_e32 v73, v19, v73
	v_mul_f32_e32 v108, v20, v74
	v_mul_f32_e32 v75, v21, v75
	v_cvt_pk_bf16_f32 v56, v107, v73
	v_cvt_pk_bf16_f32 v57, v108, v75
	v_cmp_lt_i32_e64 s[4:5], v50, v48
	global_store_dwordx2 v[88:89], v[56:57], off offset:2048
	s_waitcnt lgkmcnt(0)
	v_add_f32_e32 v55, v55, v58
	v_cndmask_b32_e64 v57, v1, v50, s[4:5]
	v_lshlrev_b32_e32 v57, 2, v57
	ds_bpermute_b32 v57, v57, v55
	v_cmp_lt_i32_e64 s[4:5], v51, v48
	v_mul_f32_e32 v56, v22, v76
	v_mul_f32_e32 v58, v23, v77
	v_cvt_pk_bf16_f32 v56, v56, v58
	s_waitcnt lgkmcnt(0)
	v_add_f32_e32 v55, v55, v57
	v_cndmask_b32_e64 v57, v1, v51, s[4:5]
	v_lshlrev_b32_e32 v57, 2, v57
	ds_bpermute_b32 v60, v57, v55
	v_mul_f32_e32 v58, v24, v78
	v_cmp_lt_i32_e64 s[4:5], v52, v48
	v_mul_f32_e32 v59, v25, v79
	v_cvt_pk_bf16_f32 v57, v58, v59
	s_waitcnt lgkmcnt(0)
	v_add_f32_e32 v55, v55, v60
	v_cndmask_b32_e64 v58, v1, v52, s[4:5]
	v_lshlrev_b32_e32 v58, 2, v58
	ds_bpermute_b32 v58, v58, v55
	v_cmp_lt_i32_e64 s[4:5], v53, v48
	global_store_dwordx2 v[88:89], v[56:57], off offset:2560
	v_mul_f32_e32 v56, v26, v80
	v_mul_f32_e32 v57, v27, v81
	s_waitcnt lgkmcnt(0)
	v_add_f32_e32 v55, v55, v58
	v_cndmask_b32_e64 v58, v1, v53, s[4:5]
	v_cvt_pk_bf16_f32 v56, v56, v57
	v_mul_f32_e32 v57, v28, v82
	v_mul_f32_e32 v59, v29, v83
	v_lshlrev_b32_e32 v58, 2, v58
	v_cvt_pk_bf16_f32 v57, v57, v59
	ds_bpermute_b32 v59, v58, v55
	global_store_dwordx2 v[88:89], v[56:57], off offset:3072
	v_mul_f32_e32 v56, v30, v84
	v_cmp_lt_i32_e64 s[4:5], v54, v48
	v_mul_f32_e32 v57, v31, v85
	v_cvt_pk_bf16_f32 v58, v56, v57
	s_waitcnt lgkmcnt(0)
	v_add_f32_e32 v55, v55, v59
	v_cndmask_b32_e64 v56, v1, v54, s[4:5]
	v_lshlrev_b32_e32 v56, 2, v56
	ds_bpermute_b32 v56, v56, v55
	v_mul_f32_e32 v59, v33, v87
	v_mul_f32_e32 v57, v32, v86
	v_cvt_pk_bf16_f32 v59, v57, v59
	global_store_dwordx2 v[88:89], v[58:59], off offset:3584
	s_and_saveexec_b64 s[4:5], vcc
	v_lshl_add_u64 v[58:59], v[222:223], 2, s[6:7]
	s_waitcnt lgkmcnt(0)
	v_add_f32_e32 v35, v55, v56
	global_store_dword v[58:59], v35, off
	s_or_b64 exec, exec, s[4:5]
	v_add_u32_e32 v220, 0x1800, v34
	v_mov_b32_e32 v221, 0
	v_lshlrev_b64 v[56:57], 13, v[220:221]
	v_lshl_add_u64 v[84:85], s[8:9], 0, v[56:57]
	v_lshl_add_u64 v[72:73], v[84:85], 0, v[36:37]
	global_load_dwordx4 v[56:59], v[72:73], off
	global_load_dwordx4 v[60:63], v[72:73], off offset:1024
	global_load_dwordx4 v[64:67], v[72:73], off offset:2048
	global_load_dwordx4 v[68:71], v[72:73], off offset:3072
	v_lshl_add_u64 v[72:73], v[84:85], 0, v[40:41]
	global_load_dwordx4 v[72:75], v[72:73], off
	v_lshl_add_u64 v[76:77], v[84:85], 0, v[42:43]
	global_load_dwordx4 v[76:79], v[76:77], off
	v_lshl_add_u64 v[80:81], v[84:85], 0, v[44:45]
	global_load_dwordx4 v[80:83], v[80:81], off
	v_lshl_add_u64 v[84:85], v[84:85], 0, v[46:47]
	global_load_dwordx4 v[84:87], v[84:85], off
	v_add_u32_e32 v222, 0x800, v34
	v_mov_b32_e32 v223, 0
	v_lshlrev_b64 v[88:89], 12, v[222:223]
	v_lshl_add_u64 v[88:89], v[38:39], 0, v[88:89]
	v_cmp_lt_i32_e64 s[4:5], v49, v48
	s_waitcnt vmcnt(32)
	v_mul_f32_e32 v55, v157, v157
	v_mul_f32_e32 v90, v159, v159
	s_waitcnt vmcnt(31)
	v_mul_f32_e32 v93, v161, v161
	v_mul_f32_e32 v94, v163, v163
	s_waitcnt vmcnt(30)
	v_mul_f32_e32 v97, v165, v165
	v_mul_f32_e32 v98, v167, v167
	v_fmac_f32_e32 v55, v156, v156
	v_fmac_f32_e32 v90, v158, v158
	v_fmac_f32_e32 v93, v160, v160
	v_fmac_f32_e32 v94, v162, v162
	v_mul_f32_e32 v91, v2, v156
	v_mul_f32_e32 v157, v3, v157
	v_mul_f32_e32 v92, v4, v158
	v_mul_f32_e32 v159, v5, v159
	s_waitcnt vmcnt(29)
	v_mul_f32_e32 v101, v169, v169
	v_mul_f32_e32 v102, v171, v171
	v_fmac_f32_e32 v97, v164, v164
	v_fmac_f32_e32 v98, v166, v166
	v_cvt_pk_bf16_f32 v156, v91, v157
	v_add_f32_e32 v55, v55, v90
	v_add_f32_e32 v158, v93, v94
	v_mul_f32_e32 v95, v6, v160
	v_mul_f32_e32 v161, v7, v161
	s_waitcnt vmcnt(28)
	v_mul_f32_e32 v105, v173, v173
	v_mul_f32_e32 v106, v175, v175
	v_fmac_f32_e32 v101, v168, v168
	v_fmac_f32_e32 v102, v170, v170
	v_cvt_pk_bf16_f32 v157, v92, v159
	global_store_dwordx2 v[88:89], v[156:157], off
	v_cvt_pk_bf16_f32 v156, v95, v161
	v_add_f32_e32 v159, v97, v98
	v_add_f32_e32 v55, v55, v158
	v_mul_f32_e32 v96, v8, v162
	v_mul_f32_e32 v163, v9, v163
	v_mul_f32_e32 v99, v10, v164
	v_mul_f32_e32 v165, v11, v165
	s_waitcnt vmcnt(28)
; __device__ __forceinline__ unsigned cvt_pk_bf16(float lo, float hi) { unsigned r; asm volatile("v_cvt_pk_bf16_f32 %0, %1, %2" : "=v"(r) : "v"(lo), "v"(hi)); return r; }
; __device__ void phase_prep(float* ldsf) {
;     ...
;     for (int row = blockIdx.x * 8 + wave; row < M_TOK; row += gridDim.x * 8) {
;         const float4* xr = (const float4*)(x + (size_t)row * DM);
;         float4 xv[8];
; #pragma unroll
;         for (int i = 0; i < 8; ++i) xv[i] = xr[i * 64 + lane];
;         float ss = 0.f;
; #pragma unroll
;         for (int i = 0; i < 8; ++i) { const int idx = i * 64 + lane; const float4 v = xv[i];
;             ss += (v.x * v.x + v.y * v.y) + (v.z * v.z + v.w * v.w);
;             u32x2 w; w.x = cvt_pk_bf16(v.x * gq[i].x, v.y * gq[i].y); w.y = cvt_pk_bf16(v.z * gq[i].z, v.w * gq[i].w);
;             *(u32x2*)(hbf + (size_t)row * DM + idx * 4) = w; }
; #pragma unroll
;         for (int o = 32; o >= 1; o >>= 1) ss += __shfl_xor(ss, o);
;         if (lane == 0) rowss[row] = ss;
	v_mul_f32_e32 v109, v177, v177
	v_mul_f32_e32 v110, v179, v179
	v_fmac_f32_e32 v105, v172, v172
	v_fmac_f32_e32 v106, v174, v174
	v_cvt_pk_bf16_f32 v157, v96, v163
	v_add_f32_e32 v160, v101, v102
	global_store_dwordx2 v[88:89], v[156:157], off offset:512
	v_cvt_pk_bf16_f32 v156, v99, v165
	v_add_f32_e32 v55, v55, v159
	v_mul_f32_e32 v100, v12, v166
	v_mul_f32_e32 v167, v13, v167
	v_mul_f32_e32 v103, v14, v168
	v_mul_f32_e32 v169, v15, v169
	s_waitcnt vmcnt(28)
	v_mul_f32_e32 v111, v181, v181
	v_mul_f32_e32 v112, v183, v183
	v_fmac_f32_e32 v109, v176, v176
	v_fmac_f32_e32 v110, v178, v178
	v_add_f32_e32 v161, v105, v106
	v_cvt_pk_bf16_f32 v157, v100, v167
	global_store_dwordx2 v[88:89], v[156:157], off offset:1024
	v_cvt_pk_bf16_f32 v156, v103, v169
	v_add_f32_e32 v55, v55, v160
	v_mul_f32_e32 v104, v16, v170
	v_mul_f32_e32 v171, v17, v171
	s_waitcnt vmcnt(28)
	v_mul_f32_e32 v113, v185, v185
	v_fmac_f32_e32 v111, v180, v180
	v_fmac_f32_e32 v112, v182, v182
	v_add_f32_e32 v162, v109, v110
	v_cvt_pk_bf16_f32 v157, v104, v171
	global_store_dwordx2 v[88:89], v[156:157], off offset:1536
	v_add_f32_e32 v55, v55, v161
	v_mul_f32_e32 v156, v187, v187
	v_fmac_f32_e32 v113, v184, v184
	v_add_f32_e32 v163, v111, v112
	v_add_f32_e32 v55, v55, v162
	v_fmac_f32_e32 v156, v186, v186
	v_add_f32_e32 v55, v55, v163
	v_add_f32_e32 v156, v113, v156
	v_add_f32_e32 v55, v55, v156
	v_cndmask_b32_e64 v156, v1, v49, s[4:5]
	v_lshlrev_b32_e32 v156, 2, v156
	ds_bpermute_b32 v158, v156, v55
	v_mul_f32_e32 v107, v18, v172
	v_mul_f32_e32 v173, v19, v173
	v_mul_f32_e32 v108, v20, v174
	v_mul_f32_e32 v175, v21, v175
	v_cvt_pk_bf16_f32 v156, v107, v173
	v_cvt_pk_bf16_f32 v157, v108, v175
	v_cmp_lt_i32_e64 s[4:5], v50, v48
	global_store_dwordx2 v[88:89], v[156:157], off offset:2048
	s_waitcnt lgkmcnt(0)
	v_add_f32_e32 v55, v55, v158
	v_cndmask_b32_e64 v157, v1, v50, s[4:5]
	v_lshlrev_b32_e32 v157, 2, v157
	ds_bpermute_b32 v157, v157, v55
	v_cmp_lt_i32_e64 s[4:5], v51, v48
	v_mul_f32_e32 v156, v22, v176
	v_mul_f32_e32 v158, v23, v177
	v_cvt_pk_bf16_f32 v156, v156, v158
	s_waitcnt lgkmcnt(0)
	v_add_f32_e32 v55, v55, v157
	v_cndmask_b32_e64 v157, v1, v51, s[4:5]
	v_lshlrev_b32_e32 v157, 2, v157
	ds_bpermute_b32 v160, v157, v55
	v_mul_f32_e32 v158, v24, v178
	v_cmp_lt_i32_e64 s[4:5], v52, v48
	v_mul_f32_e32 v159, v25, v179
	v_cvt_pk_bf16_f32 v157, v158, v159
	s_waitcnt lgkmcnt(0)
	v_add_f32_e32 v55, v55, v160
	v_cndmask_b32_e64 v158, v1, v52, s[4:5]
	v_lshlrev_b32_e32 v158, 2, v158
	ds_bpermute_b32 v158, v158, v55
	v_cmp_lt_i32_e64 s[4:5], v53, v48
	global_store_dwordx2 v[88:89], v[156:157], off offset:2560
	v_mul_f32_e32 v156, v26, v180
	v_mul_f32_e32 v157, v27, v181
	s_waitcnt lgkmcnt(0)
	v_add_f32_e32 v55, v55, v158
	v_cndmask_b32_e64 v158, v1, v53, s[4:5]
	v_cvt_pk_bf16_f32 v156, v156, v157
	v_mul_f32_e32 v157, v28, v182
	v_mul_f32_e32 v159, v29, v183
	v_lshlrev_b32_e32 v158, 2, v158
	v_cvt_pk_bf16_f32 v157, v157, v159
	ds_bpermute_b32 v159, v158, v55
	global_store_dwordx2 v[88:89], v[156:157], off offset:3072
	v_mul_f32_e32 v156, v30, v184
	v_cmp_lt_i32_e64 s[4:5], v54, v48
	v_mul_f32_e32 v157, v31, v185
	v_cvt_pk_bf16_f32 v158, v156, v157
	s_waitcnt lgkmcnt(0)
	v_add_f32_e32 v55, v55, v159
	v_cndmask_b32_e64 v156, v1, v54, s[4:5]
	v_lshlrev_b32_e32 v156, 2, v156
	ds_bpermute_b32 v156, v156, v55
	v_mul_f32_e32 v159, v33, v187
	v_mul_f32_e32 v157, v32, v186
	v_cvt_pk_bf16_f32 v159, v157, v159
	global_store_dwordx2 v[88:89], v[158:159], off offset:3584
	s_and_saveexec_b64 s[4:5], vcc
	v_lshl_add_u64 v[158:159], v[222:223], 2, s[6:7]
	s_waitcnt lgkmcnt(0)
	v_add_f32_e32 v35, v55, v156
	global_store_dword v[158:159], v35, off
	s_or_b64 exec, exec, s[4:5]
	v_add_u32_e32 v222, 0x1000, v34
	v_mov_b32_e32 v223, 0
	v_lshlrev_b64 v[88:89], 12, v[222:223]
	v_lshl_add_u64 v[88:89], v[38:39], 0, v[88:89]
	v_cmp_lt_i32_e64 s[4:5], v49, v48
	s_waitcnt vmcnt(33)
	v_mul_f32_e32 v55, v189, v189
	v_mul_f32_e32 v90, v191, v191
	s_waitcnt vmcnt(32)
	v_mul_f32_e32 v93, v193, v193
	v_mul_f32_e32 v94, v195, v195
	s_waitcnt vmcnt(31)
	v_mul_f32_e32 v97, v197, v197
	v_mul_f32_e32 v98, v199, v199
	v_fmac_f32_e32 v55, v188, v188
	v_fmac_f32_e32 v90, v190, v190
	v_fmac_f32_e32 v93, v192, v192
	v_fmac_f32_e32 v94, v194, v194
	v_mul_f32_e32 v91, v2, v188
	v_mul_f32_e32 v189, v3, v189
	v_mul_f32_e32 v92, v4, v190
	v_mul_f32_e32 v191, v5, v191
	s_waitcnt vmcnt(30)
	v_mul_f32_e32 v101, v201, v201
	v_mul_f32_e32 v102, v203, v203
	v_fmac_f32_e32 v97, v196, v196
	v_fmac_f32_e32 v98, v198, v198
	v_cvt_pk_bf16_f32 v188, v91, v189
	v_add_f32_e32 v55, v55, v90
	v_add_f32_e32 v190, v93, v94
	v_mul_f32_e32 v95, v6, v192
	v_mul_f32_e32 v193, v7, v193
	s_waitcnt vmcnt(29)
	v_mul_f32_e32 v105, v205, v205
	v_mul_f32_e32 v106, v207, v207
	v_fmac_f32_e32 v101, v200, v200
	v_fmac_f32_e32 v102, v202, v202
	v_cvt_pk_bf16_f32 v189, v92, v191
	global_store_dwordx2 v[88:89], v[188:189], off
	v_cvt_pk_bf16_f32 v188, v95, v193
	v_add_f32_e32 v191, v97, v98
	v_add_f32_e32 v55, v55, v190
	v_mul_f32_e32 v96, v8, v194
	v_mul_f32_e32 v195, v9, v195
	v_mul_f32_e32 v99, v10, v196
	v_mul_f32_e32 v197, v11, v197
	s_waitcnt vmcnt(29)
	v_mul_f32_e32 v109, v209, v209
	v_mul_f32_e32 v110, v211, v211
	v_fmac_f32_e32 v105, v204, v204
	v_fmac_f32_e32 v106, v206, v206
	v_cvt_pk_bf16_f32 v189, v96, v195
	v_add_f32_e32 v192, v101, v102
	global_store_dwordx2 v[88:89], v[188:189], off offset:512
	v_cvt_pk_bf16_f32 v188, v99, v197
	v_add_f32_e32 v55, v55, v191
	v_mul_f32_e32 v100, v12, v198
	v_mul_f32_e32 v199, v13, v199
	v_mul_f32_e32 v103, v14, v200
	v_mul_f32_e32 v201, v15, v201
	s_waitcnt vmcnt(29)
; __device__ __forceinline__ unsigned cvt_pk_bf16(float lo, float hi) { unsigned r; asm volatile("v_cvt_pk_bf16_f32 %0, %1, %2" : "=v"(r) : "v"(lo), "v"(hi)); return r; }
; __device__ void phase_prep(float* ldsf) {
;     ...
;     for (int row = blockIdx.x * 8 + wave; row < M_TOK; row += gridDim.x * 8) {
;         const float4* xr = (const float4*)(x + (size_t)row * DM);
;         float4 xv[8];
; #pragma unroll
;         for (int i = 0; i < 8; ++i) xv[i] = xr[i * 64 + lane];
;         float ss = 0.f;
; #pragma unroll
;         for (int i = 0; i < 8; ++i) { const int idx = i * 64 + lane; const float4 v = xv[i];
;             ss += (v.x * v.x + v.y * v.y) + (v.z * v.z + v.w * v.w);
;             u32x2 w; w.x = cvt_pk_bf16(v.x * gq[i].x, v.y * gq[i].y); w.y = cvt_pk_bf16(v.z * gq[i].z, v.w * gq[i].w);
;             *(u32x2*)(hbf + (size_t)row * DM + idx * 4) = w; }
; #pragma unroll
;         for (int o = 32; o >= 1; o >>= 1) ss += __shfl_xor(ss, o);
;         if (lane == 0) rowss[row] = ss;
	v_mul_f32_e32 v111, v213, v213
	v_mul_f32_e32 v112, v215, v215
	v_fmac_f32_e32 v109, v208, v208
	v_fmac_f32_e32 v110, v210, v210
	v_add_f32_e32 v193, v105, v106
	v_cvt_pk_bf16_f32 v189, v100, v199
	global_store_dwordx2 v[88:89], v[188:189], off offset:1024
	v_cvt_pk_bf16_f32 v188, v103, v201
	v_add_f32_e32 v55, v55, v192
	v_mul_f32_e32 v104, v16, v202
	v_mul_f32_e32 v203, v17, v203
	s_waitcnt vmcnt(29)
	v_mul_f32_e32 v113, v217, v217
	v_fmac_f32_e32 v111, v212, v212
	v_fmac_f32_e32 v112, v214, v214
	v_add_f32_e32 v194, v109, v110
	v_cvt_pk_bf16_f32 v189, v104, v203
	global_store_dwordx2 v[88:89], v[188:189], off offset:1536
	v_add_f32_e32 v55, v55, v193
	v_mul_f32_e32 v188, v219, v219
	v_fmac_f32_e32 v113, v216, v216
	v_add_f32_e32 v195, v111, v112
	v_add_f32_e32 v55, v55, v194
	v_fmac_f32_e32 v188, v218, v218
	v_add_f32_e32 v55, v55, v195
	v_add_f32_e32 v188, v113, v188
	v_add_f32_e32 v55, v55, v188
	v_cndmask_b32_e64 v188, v1, v49, s[4:5]
	v_lshlrev_b32_e32 v188, 2, v188
	ds_bpermute_b32 v190, v188, v55
	v_mul_f32_e32 v107, v18, v204
	v_mul_f32_e32 v205, v19, v205
	v_mul_f32_e32 v108, v20, v206
	v_mul_f32_e32 v207, v21, v207
	v_cvt_pk_bf16_f32 v188, v107, v205
	v_cvt_pk_bf16_f32 v189, v108, v207
	v_cmp_lt_i32_e64 s[4:5], v50, v48
	global_store_dwordx2 v[88:89], v[188:189], off offset:2048
	s_waitcnt lgkmcnt(0)
	v_add_f32_e32 v55, v55, v190
	v_cndmask_b32_e64 v189, v1, v50, s[4:5]
	v_lshlrev_b32_e32 v189, 2, v189
	ds_bpermute_b32 v189, v189, v55
	v_cmp_lt_i32_e64 s[4:5], v51, v48
	v_mul_f32_e32 v188, v22, v208
	v_mul_f32_e32 v190, v23, v209
	v_cvt_pk_bf16_f32 v188, v188, v190
	s_waitcnt lgkmcnt(0)
	v_add_f32_e32 v55, v55, v189
	v_cndmask_b32_e64 v189, v1, v51, s[4:5]
	v_lshlrev_b32_e32 v189, 2, v189
	ds_bpermute_b32 v192, v189, v55
	v_mul_f32_e32 v190, v24, v210
	v_cmp_lt_i32_e64 s[4:5], v52, v48
	v_mul_f32_e32 v191, v25, v211
	v_cvt_pk_bf16_f32 v189, v190, v191
	s_waitcnt lgkmcnt(0)
	v_add_f32_e32 v55, v55, v192
	v_cndmask_b32_e64 v190, v1, v52, s[4:5]
	v_lshlrev_b32_e32 v190, 2, v190
	ds_bpermute_b32 v190, v190, v55
	v_cmp_lt_i32_e64 s[4:5], v53, v48
	global_store_dwordx2 v[88:89], v[188:189], off offset:2560
	v_mul_f32_e32 v188, v26, v212
	v_mul_f32_e32 v189, v27, v213
	s_waitcnt lgkmcnt(0)
	v_add_f32_e32 v55, v55, v190
	v_cndmask_b32_e64 v190, v1, v53, s[4:5]
	v_cvt_pk_bf16_f32 v188, v188, v189
	v_mul_f32_e32 v189, v28, v214
	v_mul_f32_e32 v191, v29, v215
	v_lshlrev_b32_e32 v190, 2, v190
	v_cvt_pk_bf16_f32 v189, v189, v191
	ds_bpermute_b32 v191, v190, v55
	global_store_dwordx2 v[88:89], v[188:189], off offset:3072
	v_mul_f32_e32 v188, v30, v216
	v_cmp_lt_i32_e64 s[4:5], v54, v48
	v_mul_f32_e32 v189, v31, v217
	v_cvt_pk_bf16_f32 v190, v188, v189
	s_waitcnt lgkmcnt(0)
	v_add_f32_e32 v55, v55, v191
	v_cndmask_b32_e64 v188, v1, v54, s[4:5]
	v_lshlrev_b32_e32 v188, 2, v188
	ds_bpermute_b32 v188, v188, v55
	v_mul_f32_e32 v191, v33, v219
	v_mul_f32_e32 v189, v32, v218
	v_cvt_pk_bf16_f32 v191, v189, v191
	global_store_dwordx2 v[88:89], v[190:191], off offset:3584
	s_and_saveexec_b64 s[4:5], vcc
	v_lshl_add_u64 v[190:191], v[222:223], 2, s[6:7]
	s_waitcnt lgkmcnt(0)
	v_add_f32_e32 v35, v55, v188
	global_store_dword v[190:191], v35, off
	s_or_b64 exec, exec, s[4:5]
	v_add_u32_e32 v222, 0x1800, v34
	v_mov_b32_e32 v223, 0
	v_lshlrev_b64 v[88:89], 12, v[222:223]
	v_lshl_add_u64 v[88:89], v[38:39], 0, v[88:89]
	v_cmp_lt_i32_e64 s[4:5], v49, v48
	s_waitcnt vmcnt(25)
	v_mul_f32_e32 v55, v57, v57
	v_mul_f32_e32 v90, v59, v59
	s_waitcnt vmcnt(24)
	v_mul_f32_e32 v93, v61, v61
	v_mul_f32_e32 v94, v63, v63
	s_waitcnt vmcnt(23)
	v_mul_f32_e32 v97, v65, v65
	v_mul_f32_e32 v98, v67, v67
	v_fmac_f32_e32 v55, v56, v56
	v_fmac_f32_e32 v90, v58, v58
	v_fmac_f32_e32 v93, v60, v60
	v_fmac_f32_e32 v94, v62, v62
	v_mul_f32_e32 v91, v2, v56
	v_mul_f32_e32 v57, v3, v57
	v_mul_f32_e32 v92, v4, v58
	v_mul_f32_e32 v59, v5, v59
	s_waitcnt vmcnt(22)
	v_mul_f32_e32 v101, v69, v69
	v_mul_f32_e32 v102, v71, v71
	v_fmac_f32_e32 v97, v64, v64
	v_fmac_f32_e32 v98, v66, v66
	v_cvt_pk_bf16_f32 v56, v91, v57
	v_add_f32_e32 v55, v55, v90
	v_add_f32_e32 v58, v93, v94
	v_mul_f32_e32 v95, v6, v60
	v_mul_f32_e32 v61, v7, v61
	s_waitcnt vmcnt(21)
; __device__ __forceinline__ unsigned cvt_pk_bf16(float lo, float hi) { unsigned r; asm volatile("v_cvt_pk_bf16_f32 %0, %1, %2" : "=v"(r) : "v"(lo), "v"(hi)); return r; }
; __device__ void phase_prep(float* ldsf) {
;     ...
;     for (int row = blockIdx.x * 8 + wave; row < M_TOK; row += gridDim.x * 8) {
;         const float4* xr = (const float4*)(x + (size_t)row * DM);
;         float4 xv[8];
; #pragma unroll
;         for (int i = 0; i < 8; ++i) xv[i] = xr[i * 64 + lane];
;         float ss = 0.f;
; #pragma unroll
;         for (int i = 0; i < 8; ++i) { const int idx = i * 64 + lane; const float4 v = xv[i];
;             ss += (v.x * v.x + v.y * v.y) + (v.z * v.z + v.w * v.w);
;             u32x2 w; w.x = cvt_pk_bf16(v.x * gq[i].x, v.y * gq[i].y); w.y = cvt_pk_bf16(v.z * gq[i].z, v.w * gq[i].w);
;             *(u32x2*)(hbf + (size_t)row * DM + idx * 4) = w; }
; #pragma unroll
;         for (int o = 32; o >= 1; o >>= 1) ss += __shfl_xor(ss, o);
;         if (lane == 0) rowss[row] = ss;
	v_mul_f32_e32 v105, v73, v73
	v_mul_f32_e32 v106, v75, v75
	v_fmac_f32_e32 v101, v68, v68
	v_fmac_f32_e32 v102, v70, v70
	v_cvt_pk_bf16_f32 v57, v92, v59
	global_store_dwordx2 v[88:89], v[56:57], off
	v_cvt_pk_bf16_f32 v56, v95, v61
	v_add_f32_e32 v59, v97, v98
	v_add_f32_e32 v55, v55, v58
	v_mul_f32_e32 v96, v8, v62
	v_mul_f32_e32 v63, v9, v63
	v_mul_f32_e32 v99, v10, v64
	v_mul_f32_e32 v65, v11, v65
	s_waitcnt vmcnt(21)
	v_mul_f32_e32 v109, v77, v77
	v_mul_f32_e32 v110, v79, v79
	v_fmac_f32_e32 v105, v72, v72
	v_fmac_f32_e32 v106, v74, v74
	v_cvt_pk_bf16_f32 v57, v96, v63
	v_add_f32_e32 v60, v101, v102
	global_store_dwordx2 v[88:89], v[56:57], off offset:512
	v_cvt_pk_bf16_f32 v56, v99, v65
	v_add_f32_e32 v55, v55, v59
	v_mul_f32_e32 v100, v12, v66
	v_mul_f32_e32 v67, v13, v67
	v_mul_f32_e32 v103, v14, v68
	v_mul_f32_e32 v69, v15, v69
	s_waitcnt vmcnt(21)
	v_mul_f32_e32 v111, v81, v81
	v_mul_f32_e32 v112, v83, v83
	v_fmac_f32_e32 v109, v76, v76
	v_fmac_f32_e32 v110, v78, v78
	v_add_f32_e32 v61, v105, v106
	v_cvt_pk_bf16_f32 v57, v100, v67
	global_store_dwordx2 v[88:89], v[56:57], off offset:1024
	v_cvt_pk_bf16_f32 v56, v103, v69
	v_add_f32_e32 v55, v55, v60
	v_mul_f32_e32 v104, v16, v70
	v_mul_f32_e32 v71, v17, v71
	s_waitcnt vmcnt(21)
	v_mul_f32_e32 v113, v85, v85
	v_fmac_f32_e32 v111, v80, v80
	v_fmac_f32_e32 v112, v82, v82
	v_add_f32_e32 v62, v109, v110
	v_cvt_pk_bf16_f32 v57, v104, v71
	global_store_dwordx2 v[88:89], v[56:57], off offset:1536
	v_add_f32_e32 v55, v55, v61
	v_mul_f32_e32 v56, v87, v87
	v_fmac_f32_e32 v113, v84, v84
	v_add_f32_e32 v63, v111, v112
	v_add_f32_e32 v55, v55, v62
	v_fmac_f32_e32 v56, v86, v86
	v_add_f32_e32 v55, v55, v63
	v_add_f32_e32 v56, v113, v56
	v_add_f32_e32 v55, v55, v56
	v_cndmask_b32_e64 v56, v1, v49, s[4:5]
	v_lshlrev_b32_e32 v56, 2, v56
	ds_bpermute_b32 v58, v56, v55
	v_mul_f32_e32 v107, v18, v72
	v_mul_f32_e32 v73, v19, v73
	v_mul_f32_e32 v108, v20, v74
	v_mul_f32_e32 v75, v21, v75
	v_cvt_pk_bf16_f32 v56, v107, v73
	v_cvt_pk_bf16_f32 v57, v108, v75
	v_cmp_lt_i32_e64 s[4:5], v50, v48
	global_store_dwordx2 v[88:89], v[56:57], off offset:2048
	s_waitcnt lgkmcnt(0)
	v_add_f32_e32 v55, v55, v58
	v_cndmask_b32_e64 v57, v1, v50, s[4:5]
	v_lshlrev_b32_e32 v57, 2, v57
	ds_bpermute_b32 v57, v57, v55
	v_cmp_lt_i32_e64 s[4:5], v51, v48
	v_mul_f32_e32 v56, v22, v76
	v_mul_f32_e32 v58, v23, v77
	v_cvt_pk_bf16_f32 v56, v56, v58
	s_waitcnt lgkmcnt(0)
	v_add_f32_e32 v55, v55, v57
	v_cndmask_b32_e64 v57, v1, v51, s[4:5]
	v_lshlrev_b32_e32 v57, 2, v57
	ds_bpermute_b32 v60, v57, v55
	v_mul_f32_e32 v58, v24, v78
	v_cmp_lt_i32_e64 s[4:5], v52, v48
	v_mul_f32_e32 v59, v25, v79
	v_cvt_pk_bf16_f32 v57, v58, v59
	s_waitcnt lgkmcnt(0)
	v_add_f32_e32 v55, v55, v60
	v_cndmask_b32_e64 v58, v1, v52, s[4:5]
	v_lshlrev_b32_e32 v58, 2, v58
	ds_bpermute_b32 v58, v58, v55
	v_cmp_lt_i32_e64 s[4:5], v53, v48
	global_store_dwordx2 v[88:89], v[56:57], off offset:2560
	v_mul_f32_e32 v56, v26, v80
	v_mul_f32_e32 v57, v27, v81
	s_waitcnt lgkmcnt(0)
	v_add_f32_e32 v55, v55, v58
	v_cndmask_b32_e64 v58, v1, v53, s[4:5]
	v_cvt_pk_bf16_f32 v56, v56, v57
	v_mul_f32_e32 v57, v28, v82
	v_mul_f32_e32 v59, v29, v83
	v_lshlrev_b32_e32 v58, 2, v58
	v_cvt_pk_bf16_f32 v57, v57, v59
	ds_bpermute_b32 v59, v58, v55
	global_store_dwordx2 v[88:89], v[56:57], off offset:3072
	v_mul_f32_e32 v56, v30, v84
	v_cmp_lt_i32_e64 s[4:5], v54, v48
	v_mul_f32_e32 v57, v31, v85
	v_cvt_pk_bf16_f32 v58, v56, v57
	s_waitcnt lgkmcnt(0)
	v_add_f32_e32 v55, v55, v59
	v_cndmask_b32_e64 v56, v1, v54, s[4:5]
	v_lshlrev_b32_e32 v56, 2, v56
	ds_bpermute_b32 v56, v56, v55
	v_mul_f32_e32 v59, v33, v87
	v_mul_f32_e32 v57, v32, v86
	v_cvt_pk_bf16_f32 v59, v57, v59
	global_store_dwordx2 v[88:89], v[58:59], off offset:3584
	s_and_saveexec_b64 s[4:5], vcc
	v_lshl_add_u64 v[58:59], v[222:223], 2, s[6:7]
	s_waitcnt lgkmcnt(0)
	v_add_f32_e32 v35, v55, v56
	global_store_dword v[58:59], v35, off
	s_or_b64 exec, exec, s[4:5]
	s_branch .LBB0_83
